# gain-scaled weight transposes (P0 tr_item, P3 copy): eight gain dwords fetched together instead of four serial waited pairs
# baseline (speedup 1.0000x reference)
; #define LAS __attribute__((address_space(3)))
; __device__ __forceinline__ void tr_item(const float* __restrict__ W, int ldw, int K, bf16* __restrict__ WT, int nblk, int mapmode, const float* __restrict__ ksc, LAS float* scr, int item, int lane) {
;     const int kb = item / nblk, nb = item - kb * nblk, k0 = 64 * kb, n0 = 32 * nb;
;     const int L = (n0 & ~255) + 64 * ((n0 >> 5) & 3) + 32 * ((n0 >> 7) & 1);
;     const int src0 = mapmode ? ((L >> 5) & 1) * DFF + 128 * (L >> 8) + 32 * ((L >> 6) & 3) : L;
;     f32x4 v[8];
; #pragma unroll
;     for (int i = 0; i < 8; ++i) { const int kk = 8 * i + (lane >> 3); v[i] = __builtin_nontemporal_load((const f32x4*)(W + (size_t)(k0 + kk) * ldw + src0 + 4 * (lane & 7))); }
; #pragma unroll
;     for (int i = 0; i < 8; ++i) { const int kk = 8 * i + (lane >> 3); f32x4 w = v[i]; if (ksc) w *= ksc[k0 + kk];
;         LAS float* d = scr + kk * 33 + 4 * (lane & 7); d[0] = w[0]; d[1] = w[1]; d[2] = w[2]; d[3] = w[3]; }
.LBB0_41:
	s_ashr_i32 s10, s27, 31
	s_lshr_b32 s10, s10, 25
	s_add_i32 s10, s27, s10
	s_ashr_i32 s11, s10, 7
	s_mov_b64 s[4:5], s[0:1]
	s_lshl_b32 s28, s11, 12
	s_load_dwordx2 s[12:13], s[4:5], 0x18
	s_lshl_b32 s10, s11, 6
	s_sub_i32 s11, s25, s28
	s_and_b32 s16, s21, 0xc0
	s_and_b32 s17, s23, 32
	s_and_b32 s11, s11, 0xffffff00
	s_or_b32 s16, s16, s17
	s_or_b32 s16, s16, s11
	s_ashr_i32 s17, s16, 31
	s_lshl_b64 s[16:17], s[16:17], 2
	v_or_b32_e32 v44, s10, v38
	s_waitcnt lgkmcnt(0)
	s_add_u32 s12, s12, s16
	s_addc_u32 s13, s13, s17
	v_ashrrev_i32_e32 v45, 31, v44
	v_or_b32_e32 v6, 8, v44
	v_lshl_add_u64 v[2:3], s[12:13], 0, v[42:43]
	v_lshlrev_b64 v[4:5], 14, v[44:45]
	v_ashrrev_i32_e32 v7, 31, v6
	s_mov_b64 s[4:5], s[0:1]
	s_mov_b64 s[14:15], s[0:1]
	v_lshl_add_u64 v[4:5], v[2:3], 0, v[4:5]
	v_lshlrev_b64 v[6:7], 14, v[6:7]
	v_lshl_add_u64 v[6:7], v[2:3], 0, v[6:7]
	global_load_dwordx4 v[26:29], v[4:5], off nt
	global_load_dwordx4 v[30:33], v[6:7], off nt
	v_or_b32_e32 v4, 16, v44
	v_ashrrev_i32_e32 v5, 31, v4
	v_or_b32_e32 v6, 24, v44
	v_lshlrev_b64 v[4:5], 14, v[4:5]
	v_ashrrev_i32_e32 v7, 31, v6
	v_lshl_add_u64 v[4:5], v[2:3], 0, v[4:5]
	v_lshlrev_b64 v[6:7], 14, v[6:7]
	v_lshl_add_u64 v[6:7], v[2:3], 0, v[6:7]
	global_load_dwordx4 v[18:21], v[4:5], off nt
	global_load_dwordx4 v[22:25], v[6:7], off nt
	v_or_b32_e32 v4, 32, v44
	v_ashrrev_i32_e32 v5, 31, v4
	v_or_b32_e32 v6, 40, v44
	v_lshlrev_b64 v[4:5], 14, v[4:5]
	v_ashrrev_i32_e32 v7, 31, v6
	v_lshl_add_u64 v[4:5], v[2:3], 0, v[4:5]
	v_lshlrev_b64 v[6:7], 14, v[6:7]
	v_lshl_add_u64 v[6:7], v[2:3], 0, v[6:7]
	global_load_dwordx4 v[10:13], v[4:5], off nt
	global_load_dwordx4 v[14:17], v[6:7], off nt
	v_or_b32_e32 v4, 48, v44
	v_ashrrev_i32_e32 v5, 31, v4
	v_lshlrev_b64 v[4:5], 14, v[4:5]
	v_lshl_add_u64 v[34:35], v[2:3], 0, v[4:5]
	v_or_b32_e32 v4, 56, v44
	v_ashrrev_i32_e32 v5, 31, v4
	v_lshlrev_b64 v[4:5], 14, v[4:5]
	v_lshl_add_u64 v[36:37], v[2:3], 0, v[4:5]
	global_load_dwordx4 v[2:5], v[34:35], off nt
	global_load_dwordx4 v[6:9], v[36:37], off nt
	s_load_dwordx2 s[14:15], s[14:15], 0x10
	s_mov_b64 s[18:19], -1
	s_waitcnt lgkmcnt(0)
	s_cmp_lg_u64 s[14:15], 0
	s_cselect_b64 s[16:17], -1, 0
	s_cmp_eq_u64 s[14:15], 0
	s_cbranch_scc1 .LBB0_43
	s_ashr_i32 s11, s10, 31
	v_lshl_add_u64 v[36:37], s[10:11], 0, v[38:39]
	v_lshl_add_u64 v[34:35], v[44:45], 2, s[14:15]
	v_lshl_add_u64 v[36:37], v[36:37], 2, s[14:15]
	global_load_dword v34, v[34:35], off
	s_mov_b64 s[18:19], 0
	global_load_dword v44, v[36:37], off offset:32
	global_load_dword v200, v[36:37], off offset:64
	global_load_dword v201, v[36:37], off offset:96
	global_load_dword v202, v[36:37], off offset:128
	global_load_dword v203, v[36:37], off offset:160
	global_load_dword v204, v[36:37], off offset:192
	global_load_dword v205, v[36:37], off offset:224
	s_waitcnt vmcnt(1)
	v_pk_mul_f32 v[46:47], v[28:29], v[34:35] op_sel_hi:[1,0]
	v_pk_mul_f32 v[48:49], v[26:27], v[34:35] op_sel_hi:[1,0]
	s_waitcnt vmcnt(0)
	v_pk_mul_f32 v[36:37], v[32:33], v[44:45] op_sel_hi:[1,0]
	v_pk_mul_f32 v[34:35], v[30:31], v[44:45] op_sel_hi:[1,0]

; #define LAS __attribute__((address_space(3)))
; __device__ __forceinline__ void tr_item(const float* __restrict__ W, int ldw, int K, bf16* __restrict__ WT, int nblk, int mapmode, const float* __restrict__ ksc, LAS float* scr, int item, int lane) {
;     ...
;     for (int i = 0; i < 8; ++i) { const int kk = 8 * i + (lane >> 3); v[i] = __builtin_nontemporal_load((const f32x4*)(W + (size_t)(k0 + kk) * ldw + src0 + 4 * (lane & 7))); }
; #pragma unroll
;     for (int i = 0; i < 8; ++i) { const int kk = 8 * i + (lane >> 3); f32x4 w = v[i]; if (ksc) w *= ksc[k0 + kk];
;         LAS float* d = scr + kk * 33 + 4 * (lane & 7); d[0] = w[0]; d[1] = w[1]; d[2] = w[2]; d[3] = w[3]; }
.LBB0_45:
	s_waitcnt vmcnt(7)
	v_add_u32_e32 v26, 0x420, v50
	ds_write2_b32 v50, v48, v49 offset1:1
	ds_write2_b32 v50, v46, v47 offset0:2 offset1:3
	ds_write2_b32 v26, v34, v35 offset1:1
	v_add_u32_e32 v26, 0x428, v50
	ds_write2_b32 v26, v36, v37 offset1:1
	v_cndmask_b32_e64 v26, 0, 1, s[16:17]
	v_cmp_ne_u32_e64 s[4:5], 1, v26
	s_andn2_b64 vcc, exec, s[16:17]
	s_mov_b64 s[16:17], -1
	s_cbranch_vccnz .LBB0_47
	s_ashr_i32 s11, s10, 31
	v_lshl_add_u64 v[26:27], s[10:11], 0, v[38:39]
	v_lshl_add_u64 v[26:27], v[26:27], 2, s[14:15]
	v_mov_b32_e32 v28, v200
	v_mov_b32_e32 v34, v201
	s_mov_b64 s[16:17], 0
	s_waitcnt vmcnt(1)
	v_pk_mul_f32 v[30:31], v[20:21], v[28:29] op_sel_hi:[1,0]
	v_pk_mul_f32 v[32:33], v[18:19], v[28:29] op_sel_hi:[1,0]
	s_waitcnt vmcnt(0)
	v_pk_mul_f32 v[28:29], v[24:25], v[34:35] op_sel_hi:[1,0]
	v_pk_mul_f32 v[26:27], v[22:23], v[34:35] op_sel_hi:[1,0]

; #define LAS __attribute__((address_space(3)))
; __device__ __forceinline__ void tr_item(const float* __restrict__ W, int ldw, int K, bf16* __restrict__ WT, int nblk, int mapmode, const float* __restrict__ ksc, LAS float* scr, int item, int lane) {
;     ...
;     for (int i = 0; i < 8; ++i) { const int kk = 8 * i + (lane >> 3); v[i] = __builtin_nontemporal_load((const f32x4*)(W + (size_t)(k0 + kk) * ldw + src0 + 4 * (lane & 7))); }
; #pragma unroll
;     for (int i = 0; i < 8; ++i) { const int kk = 8 * i + (lane >> 3); f32x4 w = v[i]; if (ksc) w *= ksc[k0 + kk];
;         LAS float* d = scr + kk * 33 + 4 * (lane & 7); d[0] = w[0]; d[1] = w[1]; d[2] = w[2]; d[3] = w[3]; }
.LBB0_49:
	s_waitcnt vmcnt(5)
	v_add_u32_e32 v18, 0x840, v50
	ds_write2_b32 v18, v32, v33 offset1:1
	v_add_u32_e32 v18, 0x848, v50
	ds_write2_b32 v18, v30, v31 offset1:1
	v_add_u32_e32 v18, 0xc60, v50
	ds_write2_b32 v18, v26, v27 offset1:1
	v_add_u32_e32 v18, 0xc68, v50
	s_and_b64 vcc, exec, s[4:5]
	s_mov_b64 s[16:17], -1
	ds_write2_b32 v18, v28, v29 offset1:1
	s_cbranch_vccnz .LBB0_51
	s_ashr_i32 s11, s10, 31
	v_lshl_add_u64 v[18:19], s[10:11], 0, v[38:39]
	v_lshl_add_u64 v[18:19], v[18:19], 2, s[14:15]
	v_mov_b32_e32 v20, v202
	v_mov_b32_e32 v26, v203
	s_mov_b64 s[16:17], 0
	s_waitcnt vmcnt(1)
	v_pk_mul_f32 v[22:23], v[12:13], v[20:21] op_sel_hi:[1,0]
	v_pk_mul_f32 v[24:25], v[10:11], v[20:21] op_sel_hi:[1,0]
	s_waitcnt vmcnt(0)
	v_pk_mul_f32 v[20:21], v[16:17], v[26:27] op_sel_hi:[1,0]
	v_pk_mul_f32 v[18:19], v[14:15], v[26:27] op_sel_hi:[1,0]

; #define LAS __attribute__((address_space(3)))
; __device__ __forceinline__ void tr_item(const float* __restrict__ W, int ldw, int K, bf16* __restrict__ WT, int nblk, int mapmode, const float* __restrict__ ksc, LAS float* scr, int item, int lane) {
;     ...
;     for (int i = 0; i < 8; ++i) { const int kk = 8 * i + (lane >> 3); v[i] = __builtin_nontemporal_load((const f32x4*)(W + (size_t)(k0 + kk) * ldw + src0 + 4 * (lane & 7))); }
; #pragma unroll
;     for (int i = 0; i < 8; ++i) { const int kk = 8 * i + (lane >> 3); f32x4 w = v[i]; if (ksc) w *= ksc[k0 + kk];
;         LAS float* d = scr + kk * 33 + 4 * (lane & 7); d[0] = w[0]; d[1] = w[1]; d[2] = w[2]; d[3] = w[3]; }
.LBB0_53:
	s_waitcnt vmcnt(3)
	v_add_u32_e32 v10, 0x1080, v50
	ds_write2_b32 v10, v24, v25 offset1:1
	v_add_u32_e32 v10, 0x1088, v50
	ds_write2_b32 v10, v22, v23 offset1:1
	v_add_u32_e32 v10, 0x14a0, v50
	ds_write2_b32 v10, v18, v19 offset1:1
	v_add_u32_e32 v10, 0x14a8, v50
	s_and_b64 vcc, exec, s[4:5]
	s_mov_b64 s[4:5], -1
	ds_write2_b32 v10, v20, v21 offset1:1
	s_cbranch_vccnz .LBB0_55
	s_ashr_i32 s11, s10, 31
	v_lshl_add_u64 v[10:11], s[10:11], 0, v[38:39]
	v_lshl_add_u64 v[10:11], v[10:11], 2, s[14:15]
	v_mov_b32_e32 v12, v204
	v_mov_b32_e32 v18, v205
	s_mov_b64 s[4:5], 0
	s_waitcnt vmcnt(1)
	v_pk_mul_f32 v[14:15], v[4:5], v[12:13] op_sel_hi:[1,0]
	v_pk_mul_f32 v[16:17], v[2:3], v[12:13] op_sel_hi:[1,0]
	s_waitcnt vmcnt(0)
	v_pk_mul_f32 v[12:13], v[8:9], v[18:19] op_sel_hi:[1,0]
	v_pk_mul_f32 v[10:11], v[6:7], v[18:19] op_sel_hi:[1,0]

; #define LAS __attribute__((address_space(3)))
; __device__ __forceinline__ void tr_item(const float* __restrict__ W, int ldw, int K, bf16* __restrict__ WT, int nblk, int mapmode, const float* __restrict__ ksc, LAS float* scr, int item, int lane) {
;     const int kb = item / nblk, nb = item - kb * nblk, k0 = 64 * kb, n0 = 32 * nb;
;     const int L = (n0 & ~255) + 64 * ((n0 >> 5) & 3) + 32 * ((n0 >> 7) & 1);
;     const int src0 = mapmode ? ((L >> 5) & 1) * DFF + 128 * (L >> 8) + 32 * ((L >> 6) & 3) : L;
;     f32x4 v[8];
; #pragma unroll
;     for (int i = 0; i < 8; ++i) { const int kk = 8 * i + (lane >> 3); v[i] = __builtin_nontemporal_load((const f32x4*)(W + (size_t)(k0 + kk) * ldw + src0 + 4 * (lane & 7))); }
; #pragma unroll
;     for (int i = 0; i < 8; ++i) { const int kk = 8 * i + (lane >> 3); f32x4 w = v[i]; if (ksc) w *= ksc[k0 + kk];
;         LAS float* d = scr + kk * 33 + 4 * (lane & 7); d[0] = w[0]; d[1] = w[1]; d[2] = w[2]; d[3] = w[3]; }
.LBB0_524:
	s_andn2_b64 vcc, exec, s[4:5]
	s_cbranch_vccnz .LBB0_542
	s_and_b32 s4, 0xffff, s41
	s_mul_hi_u32 s56, s4, 0x1745d18
	s_mul_i32 s6, s28, 0xba2f
	s_mul_i32 s4, s56, 0xb00
	s_add_i32 s6, s6, 0xfcba2c80
	s_sub_i32 s24, s42, s4
	s_mov_b64 s[4:5], s[0:1]
	s_lshr_b32 s6, s6, 17
	s_bfe_i32 s25, s28, 0x10002
	s_load_dwordx2 s[20:21], s[4:5], 0xc8
	s_and_b32 s57, s6, 0x7fc0
	s_add_i32 s6, s30, s55
	s_and_b32 s25, s25, 0xb00
	s_and_b32 s24, s24, 0xffffff80
	s_add_i32 s24, s24, s25
	s_and_b32 s25, s6, 0x60
	s_or_b32 s24, s24, s25
	s_ashr_i32 s25, s24, 31
	s_lshl_b64 s[24:25], s[24:25], 2
	v_or_b32_e32 v42, s57, v1
	s_waitcnt lgkmcnt(0)
	s_add_u32 s20, s20, s24
	s_addc_u32 s21, s21, s25
	v_mul_u32_u24_e32 v6, 0x1600, v42
	v_lshl_add_u64 v[2:3], s[20:21], 0, v[38:39]
	v_lshlrev_b32_e32 v6, 2, v6
	v_mov_b32_e32 v7, v39
	v_mad_u64_u32 v[4:5], s[20:21], v42, s38, v[2:3]
	v_lshl_add_u64 v[2:3], v[2:3], 0, v[6:7]
	v_add_co_u32_e32 v6, vcc, s39, v2
	s_mov_b64 s[4:5], s[0:1]
	s_mov_b64 s[22:23], s[0:1]
	v_addc_co_u32_e32 v7, vcc, 0, v3, vcc
	global_load_dwordx4 v[26:29], v[4:5], off nt
	global_load_dwordx4 v[30:33], v[6:7], off nt
	v_add_co_u32_e32 v4, vcc, s51, v2
	s_mov_b64 s[26:27], -1
	s_nop 0
	v_addc_co_u32_e32 v5, vcc, 0, v3, vcc
	v_add_co_u32_e32 v6, vcc, s52, v2
	v_add_lshl_u32 v41, s57, v1, 2
	s_nop 0
	v_addc_co_u32_e32 v7, vcc, 0, v3, vcc
	global_load_dwordx4 v[18:21], v[4:5], off nt
	global_load_dwordx4 v[22:25], v[6:7], off nt
	v_add_co_u32_e32 v4, vcc, s53, v2
	s_nop 1
	v_addc_co_u32_e32 v5, vcc, 0, v3, vcc
	v_add_co_u32_e32 v6, vcc, s54, v2
	s_nop 1
	v_addc_co_u32_e32 v7, vcc, 0, v3, vcc
	global_load_dwordx4 v[10:13], v[4:5], off nt
	global_load_dwordx4 v[14:17], v[6:7], off nt
	v_add_co_u32_e32 v4, vcc, 0x108000, v2
	s_nop 1
	v_addc_co_u32_e32 v5, vcc, 0, v3, vcc
	v_add_co_u32_e32 v6, vcc, 0x134000, v2
	s_nop 1
	v_addc_co_u32_e32 v7, vcc, 0, v3, vcc
	global_load_dwordx4 v[2:5], v[4:5], off nt
	s_nop 0
	global_load_dwordx4 v[6:9], v[6:7], off nt
	s_load_dwordx2 s[22:23], s[22:23], 0xc0
	s_waitcnt lgkmcnt(0)
	s_cmp_lg_u64 s[22:23], 0
	s_cselect_b64 s[24:25], -1, 0
	s_cmp_eq_u64 s[22:23], 0
	s_cbranch_scc1 .LBB0_527
	v_lshlrev_b32_e32 v34, 2, v42
	global_load_dword v34, v34, s[22:23]
	s_nop 0
	global_load_dword v68, v41, s[22:23] offset:32
	global_load_dword v70, v41, s[22:23] offset:64
	global_load_dword v71, v41, s[22:23] offset:96
	global_load_dword v72, v41, s[22:23] offset:128
	global_load_dword v73, v41, s[22:23] offset:160
	global_load_dword v74, v41, s[22:23] offset:192
	global_load_dword v75, v41, s[22:23] offset:224
	s_mov_b64 s[26:27], 0
	s_waitcnt vmcnt(0)
	v_pk_mul_f32 v[42:43], v[28:29], v[34:35] op_sel_hi:[1,0]
	v_pk_mul_f32 v[44:45], v[26:27], v[34:35] op_sel_hi:[1,0]
	v_pk_mul_f32 v[36:37], v[32:33], v[68:69] op_sel_hi:[1,0]
	v_pk_mul_f32 v[34:35], v[30:31], v[68:69] op_sel_hi:[1,0]

; #define LAS __attribute__((address_space(3)))
; __device__ __forceinline__ void tr_item(const float* __restrict__ W, int ldw, int K, bf16* __restrict__ WT, int nblk, int mapmode, const float* __restrict__ ksc, LAS float* scr, int item, int lane) {
;     ...
;     for (int i = 0; i < 8; ++i) { const int kk = 8 * i + (lane >> 3); v[i] = __builtin_nontemporal_load((const f32x4*)(W + (size_t)(k0 + kk) * ldw + src0 + 4 * (lane & 7))); }
; #pragma unroll
;     for (int i = 0; i < 8; ++i) { const int kk = 8 * i + (lane >> 3); f32x4 w = v[i]; if (ksc) w *= ksc[k0 + kk];
;         LAS float* d = scr + kk * 33 + 4 * (lane & 7); d[0] = w[0]; d[1] = w[1]; d[2] = w[2]; d[3] = w[3]; }
.LBB0_529:
	s_waitcnt vmcnt(0)
	v_cndmask_b32_e64 v26, 0, 1, s[24:25]
	v_cmp_ne_u32_e64 s[4:5], 1, v26
	s_andn2_b64 vcc, exec, s[24:25]
	s_mov_b64 s[24:25], -1
	ds_write2_b32 v51, v44, v45 offset1:1
	ds_write2_b32 v51, v42, v43 offset0:2 offset1:3
	ds_write2_b32 v52, v34, v35 offset1:1
	ds_write2_b32 v53, v36, v37 offset1:1
	s_cbranch_vccnz .LBB0_531
	v_mov_b32_e32 v26, v70
	v_mov_b32_e32 v34, v71
	s_mov_b64 s[24:25], 0
	s_waitcnt vmcnt(1)
	v_pk_mul_f32 v[30:31], v[20:21], v[26:27] op_sel_hi:[1,0]
	v_pk_mul_f32 v[32:33], v[18:19], v[26:27] op_sel_hi:[1,0]
	s_waitcnt vmcnt(0)
	v_pk_mul_f32 v[28:29], v[24:25], v[34:35] op_sel_hi:[1,0]
	v_pk_mul_f32 v[26:27], v[22:23], v[34:35] op_sel_hi:[1,0]

; #define LAS __attribute__((address_space(3)))
; __device__ __forceinline__ void tr_item(const float* __restrict__ W, int ldw, int K, bf16* __restrict__ WT, int nblk, int mapmode, const float* __restrict__ ksc, LAS float* scr, int item, int lane) {
;     ...
;     for (int i = 0; i < 8; ++i) { const int kk = 8 * i + (lane >> 3); v[i] = __builtin_nontemporal_load((const f32x4*)(W + (size_t)(k0 + kk) * ldw + src0 + 4 * (lane & 7))); }
; #pragma unroll
;     for (int i = 0; i < 8; ++i) { const int kk = 8 * i + (lane >> 3); f32x4 w = v[i]; if (ksc) w *= ksc[k0 + kk];
;         LAS float* d = scr + kk * 33 + 4 * (lane & 7); d[0] = w[0]; d[1] = w[1]; d[2] = w[2]; d[3] = w[3]; }
.LBB0_533:
	s_and_b64 vcc, exec, s[4:5]
	s_mov_b64 s[24:25], -1
	ds_write2_b32 v54, v32, v33 offset1:1
	ds_write2_b32 v55, v30, v31 offset1:1
	ds_write2_b32 v56, v26, v27 offset1:1
	ds_write2_b32 v57, v28, v29 offset1:1
	s_cbranch_vccnz .LBB0_535
	v_mov_b32_e32 v18, v72
	v_mov_b32_e32 v26, v73
	s_mov_b64 s[24:25], 0
	s_waitcnt vmcnt(1)
	v_pk_mul_f32 v[22:23], v[12:13], v[18:19] op_sel_hi:[1,0]
	v_pk_mul_f32 v[24:25], v[10:11], v[18:19] op_sel_hi:[1,0]
	s_waitcnt vmcnt(0)
	v_pk_mul_f32 v[20:21], v[16:17], v[26:27] op_sel_hi:[1,0]
	v_pk_mul_f32 v[18:19], v[14:15], v[26:27] op_sel_hi:[1,0]

; #define LAS __attribute__((address_space(3)))
; __device__ __forceinline__ void tr_item(const float* __restrict__ W, int ldw, int K, bf16* __restrict__ WT, int nblk, int mapmode, const float* __restrict__ ksc, LAS float* scr, int item, int lane) {
;     ...
;     for (int i = 0; i < 8; ++i) { const int kk = 8 * i + (lane >> 3); v[i] = __builtin_nontemporal_load((const f32x4*)(W + (size_t)(k0 + kk) * ldw + src0 + 4 * (lane & 7))); }
; #pragma unroll
;     for (int i = 0; i < 8; ++i) { const int kk = 8 * i + (lane >> 3); f32x4 w = v[i]; if (ksc) w *= ksc[k0 + kk];
;         LAS float* d = scr + kk * 33 + 4 * (lane & 7); d[0] = w[0]; d[1] = w[1]; d[2] = w[2]; d[3] = w[3]; }
.LBB0_537:
	v_add_u32_e32 v10, 0x420, v66
	ds_write2_b32 v66, v24, v25 offset1:1
	ds_write2_b32 v66, v22, v23 offset0:2 offset1:3
	ds_write2_b32 v10, v18, v19 offset1:1
	v_add_u32_e32 v10, 0x428, v66
	s_and_b64 vcc, exec, s[4:5]
	ds_write2_b32 v10, v20, v21 offset1:1
	s_cbranch_vccnz .LBB0_539
	v_mov_b32_e32 v10, v74
	v_mov_b32_e32 v18, v75
	s_waitcnt vmcnt(1)
	v_pk_mul_f32 v[14:15], v[4:5], v[10:11] op_sel_hi:[1,0]
	v_pk_mul_f32 v[16:17], v[2:3], v[10:11] op_sel_hi:[1,0]
	s_waitcnt vmcnt(0)
	v_pk_mul_f32 v[12:13], v[8:9], v[18:19] op_sel_hi:[1,0]
	v_pk_mul_f32 v[10:11], v[6:7], v[18:19] op_sel_hi:[1,0]
	s_cbranch_execz .LBB0_540
	s_branch .LBB0_541
